# cache policy: nt hint also on the 8 read-once row-chunk loads of the final RMSNorm loop; on top of v031
# baseline (speedup 1.0000x reference)
; __device__ __forceinline__ void final_phase(float* x, const float* ssq, const float* gn, bool team) {
;     ...
;     for (int m = mbeg; m < mend; m += mstep) { float s = ssq[(size_t)m * 32 + (lane & 31)];
; #pragma unroll
;         for (int o = 1; o < 32; o <<= 1) s += __shfl_xor(s, o);
;         const float rs = __builtin_amdgcn_rsqf(s * (1.0f / D) + 1e-6f); f32x4* xr = (f32x4*)(x + (size_t)m * D) + lane; const f32x4* gr = (const f32x4*)gn + lane;
; #pragma unroll
;         for (int j = 0; j < 8; ++j) xr[64 * j] = xr[64 * j] * rs * gr[64 * j]; }
.LBB0_2364:
	global_load_dword v3, v[18:19], off
	global_load_dwordx4 v[76:79], v[14:15], off offset:-4096 nt
	global_load_dwordx4 v[80:83], v[14:15], off offset:-3072 nt
	global_load_dwordx4 v[84:87], v[14:15], off offset:-2048 nt
	global_load_dwordx4 v[88:91], v[14:15], off offset:-1024 nt
	global_load_dwordx4 v[92:95], v[14:15], off nt
	global_load_dwordx4 v[96:99], v[14:15], off offset:1024 nt
	global_load_dwordx4 v[100:103], v[14:15], off offset:2048 nt
	global_load_dwordx4 v[104:107], v[14:15], off offset:3072 nt
	v_add_u32_e32 v0, v0, v2
	v_cmp_ge_i32_e32 vcc, v0, v22
	v_lshl_add_u64 v[18:19], v[18:19], 0, v[20:21]
	s_or_b64 s[0:1], vcc, s[0:1]
	s_waitcnt vmcnt(8)
	ds_bpermute_b32 v40, v23, v3
	s_waitcnt lgkmcnt(0)
	v_add_f32_e32 v3, v3, v40
	ds_bpermute_b32 v40, v24, v3
	s_waitcnt lgkmcnt(0)
	v_add_f32_e32 v3, v3, v40
	ds_bpermute_b32 v40, v25, v3
	s_waitcnt lgkmcnt(0)
	v_add_f32_e32 v3, v3, v40
	ds_bpermute_b32 v40, v26, v3
	s_waitcnt lgkmcnt(0)
	v_add_f32_e32 v3, v3, v40
	ds_bpermute_b32 v40, v27, v3
	s_waitcnt lgkmcnt(0)
	v_add_f32_e32 v3, v3, v40
	v_fmamk_f32 v3, v3, 0x3a000000, v1
	v_rsq_f32_e32 v40, v3
	s_waitcnt vmcnt(7)
	v_pk_mul_f32 v[76:77], v[76:77], v[40:41] op_sel_hi:[1,0]
	v_pk_mul_f32 v[78:79], v[78:79], v[40:41] op_sel_hi:[1,0]
	v_pk_mul_f32 v[76:77], v[44:45], v[76:77]
	v_pk_mul_f32 v[78:79], v[46:47], v[78:79]
	global_store_dwordx4 v[14:15], v[76:79], off offset:-4096 nt
	s_waitcnt vmcnt(7)
	v_pk_mul_f32 v[80:81], v[80:81], v[40:41] op_sel_hi:[1,0]
	v_pk_mul_f32 v[82:83], v[82:83], v[40:41] op_sel_hi:[1,0]
	v_pk_mul_f32 v[80:81], v[48:49], v[80:81]
	v_pk_mul_f32 v[82:83], v[50:51], v[82:83]
	global_store_dwordx4 v[14:15], v[80:83], off offset:-3072 nt
	s_waitcnt vmcnt(7)
	v_pk_mul_f32 v[84:85], v[84:85], v[40:41] op_sel_hi:[1,0]
	v_pk_mul_f32 v[86:87], v[86:87], v[40:41] op_sel_hi:[1,0]
	v_pk_mul_f32 v[84:85], v[52:53], v[84:85]
	v_pk_mul_f32 v[86:87], v[54:55], v[86:87]
	global_store_dwordx4 v[14:15], v[84:87], off offset:-2048 nt
	s_waitcnt vmcnt(7)
	v_pk_mul_f32 v[88:89], v[88:89], v[40:41] op_sel_hi:[1,0]
	v_pk_mul_f32 v[90:91], v[90:91], v[40:41] op_sel_hi:[1,0]
	v_pk_mul_f32 v[88:89], v[56:57], v[88:89]
	v_pk_mul_f32 v[90:91], v[58:59], v[90:91]
	global_store_dwordx4 v[14:15], v[88:91], off offset:-1024 nt
	s_waitcnt vmcnt(7)
	v_pk_mul_f32 v[92:93], v[92:93], v[40:41] op_sel_hi:[1,0]
	v_pk_mul_f32 v[94:95], v[94:95], v[40:41] op_sel_hi:[1,0]
	v_pk_mul_f32 v[92:93], v[60:61], v[92:93]
	v_pk_mul_f32 v[94:95], v[62:63], v[94:95]
	global_store_dwordx4 v[14:15], v[92:95], off nt
	s_waitcnt vmcnt(7)
	v_pk_mul_f32 v[96:97], v[96:97], v[40:41] op_sel_hi:[1,0]
	v_pk_mul_f32 v[98:99], v[98:99], v[40:41] op_sel_hi:[1,0]
	v_pk_mul_f32 v[96:97], v[64:65], v[96:97]
	v_pk_mul_f32 v[98:99], v[66:67], v[98:99]
	global_store_dwordx4 v[14:15], v[96:99], off offset:1024 nt
	s_waitcnt vmcnt(7)
	v_pk_mul_f32 v[100:101], v[100:101], v[40:41] op_sel_hi:[1,0]
	v_pk_mul_f32 v[102:103], v[102:103], v[40:41] op_sel_hi:[1,0]
	v_pk_mul_f32 v[100:101], v[68:69], v[100:101]
	v_pk_mul_f32 v[102:103], v[70:71], v[102:103]
	global_store_dwordx4 v[14:15], v[100:103], off offset:2048 nt
	s_waitcnt vmcnt(7)
	v_pk_mul_f32 v[104:105], v[104:105], v[40:41] op_sel_hi:[1,0]
	v_pk_mul_f32 v[106:107], v[106:107], v[40:41] op_sel_hi:[1,0]
	v_pk_mul_f32 v[104:105], v[72:73], v[104:105]
	v_pk_mul_f32 v[106:107], v[74:75], v[106:107]
	global_store_dwordx4 v[14:15], v[104:107], off offset:3072 nt
	v_lshl_add_u64 v[14:15], v[14:15], 0, v[16:17]
	s_andn2_b64 exec, exec, s[0:1]
	s_cbranch_execnz .LBB0_2364
